# prep loops (a),(c): hoisted weights read directly by their consumers (register copies and dead weight-address code removed)
# baseline (speedup 1.0000x reference)
.LBB0_315:
	s_or_b64 exec, exec, s[0:1]
	global_load_dwordx4 v[100:103], v[26:27], off offset:512
	global_load_dwordx4 v[104:107], v[26:27], off offset:1536
	s_nop 0
	s_nop 0
	s_nop 0
	s_waitcnt vmcnt(3)
	v_lshlrev_b32_e32 v28, 16, v18
	v_and_b32_e32 v29, 0xffff0000, v18
	s_nop 0
	s_waitcnt vmcnt(2)
	v_lshlrev_b32_e32 v30, 16, v22
	v_and_b32_e32 v31, 0xffff0000, v22
	v_lshlrev_b32_e32 v60, 16, v19
	v_and_b32_e32 v61, 0xffff0000, v19
	v_lshlrev_b32_e32 v48, 16, v20
	v_and_b32_e32 v49, 0xffff0000, v20
	v_lshlrev_b32_e32 v38, 16, v21
	v_and_b32_e32 v39, 0xffff0000, v21
	v_lshlrev_b32_e32 v18, 16, v4
	v_and_b32_e32 v19, 0xffff0000, v4
	v_lshlrev_b32_e32 v20, 16, v14
	v_and_b32_e32 v21, 0xffff0000, v14
	v_lshlrev_b32_e32 v66, 16, v23
	v_and_b32_e32 v67, 0xffff0000, v23
	v_lshlrev_b32_e32 v52, 16, v24
	v_and_b32_e32 v53, 0xffff0000, v24
	v_lshlrev_b32_e32 v42, 16, v25
	v_and_b32_e32 v43, 0xffff0000, v25
	v_lshlrev_b32_e32 v70, 16, v10
	v_and_b32_e32 v71, 0xffff0000, v10
	v_lshlrev_b32_e32 v62, 16, v11
	v_and_b32_e32 v63, 0xffff0000, v11
	v_lshlrev_b32_e32 v50, 16, v12
	v_and_b32_e32 v51, 0xffff0000, v12
	v_lshlrev_b32_e32 v40, 16, v13
	v_and_b32_e32 v41, 0xffff0000, v13
	v_lshlrev_b32_e32 v64, 16, v5
	v_and_b32_e32 v65, 0xffff0000, v5
	v_lshlrev_b32_e32 v54, 16, v6
	v_and_b32_e32 v55, 0xffff0000, v6
	v_lshlrev_b32_e32 v44, 16, v7
	v_and_b32_e32 v45, 0xffff0000, v7
	v_lshlrev_b32_e32 v68, 16, v15
	v_and_b32_e32 v69, 0xffff0000, v15
	v_lshlrev_b32_e32 v56, 16, v16
	v_and_b32_e32 v57, 0xffff0000, v16
	v_lshlrev_b32_e32 v46, 16, v17
	v_and_b32_e32 v47, 0xffff0000, v17
	s_waitcnt vmcnt(0)
	v_mov_b64_e32 v[10:11], v[100:101]
	v_mov_b64_e32 v[12:13], v[102:103]
	v_mov_b64_e32 v[4:5], v[104:105]
	v_mov_b64_e32 v[6:7], v[106:107]
	v_pk_mul_f32 v[22:23], v[20:21], v[30:31]
	s_nop 0
	s_nop 0
	s_nop 0
	s_nop 0
	v_pk_mul_f32 v[34:35], v[18:19], v[28:29]
	s_nop 0
	s_nop 0
	s_nop 0
	s_nop 0
	v_lshlrev_b32_e32 v78, 16, v0
	v_and_b32_e32 v79, 0xffff0000, v0
	v_pk_mul_f32 v[70:71], v[70:71], v[78:79]
	v_pk_mul_f32 v[60:61], v[64:65], v[60:61]
	v_ashrrev_i32_e32 v37, 31, v36
	v_add_u32_e32 v74, s26, v74
	s_waitcnt vmcnt(5)
	v_lshlrev_b32_e32 v80, 16, v10
	s_waitcnt vmcnt(4)
	v_lshlrev_b32_e32 v0, 16, v4
	v_and_b32_e32 v81, 0xffff0000, v10
	v_and_b32_e32 v4, 0xffff0000, v4
	v_mul_f32_e32 v10, 0xbfb8aa3b, v0
	s_waitcnt vmcnt(0)
	v_pk_mul_f32 v[22:23], v[22:23], v[92:93]
	v_exp_f32_e32 v82, v10
	v_pk_fma_f32 v[28:29], v[34:35], v[84:85], v[22:23]
	s_nop 0
	s_nop 0
	s_nop 0
	s_nop 0
	s_nop 0
	v_mul_f32_e32 v10, 0xbfb8aa3b, v4
	v_exp_f32_e32 v83, v10
	s_waitcnt vmcnt(0)
	v_pk_fma_f32 v[28:29], v[70:71], v[108:109], v[28:29]
	v_pk_add_f32 v[32:33], v[82:83], 1.0 op_sel_hi:[1,0]
	v_pk_mul_f32 v[28:29], v[28:29], v[80:81]
	v_div_scale_f32 v10, s[0:1], v33, v33, v4
	v_rcp_f32_e32 v70, v10
	s_nop 0
	v_fma_f32 v71, -v10, v70, 1.0
	v_fmac_f32_e32 v70, v71, v70
	v_div_scale_f32 v71, vcc, v4, v33, v4
	v_mul_f32_e32 v73, v71, v70
	v_fma_f32 v75, -v10, v73, v71
	v_fmac_f32_e32 v73, v75, v70
	v_fma_f32 v10, -v10, v73, v71
	v_div_fmas_f32 v10, v10, v70, v73
	v_div_fixup_f32 v33, v10, v33, v4
	v_div_scale_f32 v4, s[0:1], v32, v32, v0
	v_rcp_f32_e32 v10, v4
	s_nop 0
	v_fma_f32 v70, -v4, v10, 1.0
	v_fmac_f32_e32 v10, v70, v10
	v_div_scale_f32 v70, vcc, v0, v32, v0
	v_mul_f32_e32 v71, v70, v10
	v_fma_f32 v73, -v4, v71, v70
	v_fmac_f32_e32 v71, v73, v10
	v_fma_f32 v4, -v4, v71, v70
	v_div_fmas_f32 v4, v4, v10, v71
	v_div_fixup_f32 v32, v4, v32, v0
	v_pk_mul_f32 v[28:29], v[28:29], v[32:33]
	v_pk_mul_f32 v[32:33], v[68:69], v[66:67]
	v_lshlrev_b32_e32 v66, 16, v5
	v_and_b32_e32 v67, 0xffff0000, v5
	v_mul_f32_e32 v4, 0xbfb8aa3b, v66
	v_mul_f32_e32 v5, 0xbfb8aa3b, v67
	v_exp_f32_e32 v4, v4
	v_exp_f32_e32 v5, v5
	v_lshlrev_b32_e32 v0, 16, v1
	v_and_b32_e32 v1, 0xffff0000, v1
	v_pk_mul_f32 v[30:31], v[32:33], v[94:95]
	v_pk_mul_f32 v[0:1], v[62:63], v[0:1]
	v_pk_fma_f32 v[26:27], v[60:61], v[86:87], v[30:31]
	v_lshlrev_b32_e32 v10, 16, v11
	v_and_b32_e32 v11, 0xffff0000, v11
	v_pk_fma_f32 v[0:1], v[0:1], v[110:111], v[26:27]
	v_pk_add_f32 v[4:5], v[4:5], 1.0 op_sel_hi:[1,0]
	v_pk_mul_f32 v[0:1], v[0:1], v[10:11]
	v_div_scale_f32 v10, s[0:1], v5, v5, v67
	v_rcp_f32_e32 v11, v10
	v_pk_mul_f32 v[32:33], v[54:55], v[48:49]
	v_fma_f32 v26, -v10, v11, 1.0
	v_fmac_f32_e32 v11, v26, v11
	v_div_scale_f32 v26, vcc, v67, v5, v67
	v_mul_f32_e32 v27, v26, v11
	v_fma_f32 v30, -v10, v27, v26
	v_fmac_f32_e32 v27, v30, v11
	v_fma_f32 v10, -v10, v27, v26
	v_div_fmas_f32 v10, v10, v11, v27
	v_div_fixup_f32 v5, v10, v5, v67
	v_div_scale_f32 v10, s[0:1], v4, v4, v66
	v_rcp_f32_e32 v11, v10
	s_nop 0
	v_fma_f32 v26, -v10, v11, 1.0
	v_fmac_f32_e32 v11, v26, v11
	v_div_scale_f32 v26, vcc, v66, v4, v66
	v_mul_f32_e32 v27, v26, v11
	v_fma_f32 v30, -v10, v27, v26
	v_fmac_f32_e32 v27, v30, v11
	v_fma_f32 v10, -v10, v27, v26
	v_div_fmas_f32 v10, v10, v11, v27
	v_div_fixup_f32 v4, v10, v4, v66
	v_pk_mul_f32 v[0:1], v[4:5], v[0:1]
	v_pk_mul_f32 v[4:5], v[56:57], v[52:53]
	v_lshlrev_b32_e32 v10, 16, v2
	v_and_b32_e32 v11, 0xffff0000, v2
	v_pk_mul_f32 v[4:5], v[4:5], v[96:97]
	v_lshlrev_b32_e32 v2, 16, v6
	v_and_b32_e32 v6, 0xffff0000, v6
	v_pk_fma_f32 v[4:5], v[32:33], v[88:89], v[4:5]
	v_pk_mul_f32 v[10:11], v[50:51], v[10:11]
	v_lshlrev_b32_e32 v26, 16, v12
	v_and_b32_e32 v27, 0xffff0000, v12
	v_mul_f32_e32 v12, 0xbfb8aa3b, v2
	v_pk_fma_f32 v[4:5], v[10:11], v[112:113], v[4:5]
	v_mul_f32_e32 v10, 0xbfb8aa3b, v6
	v_exp_f32_e32 v30, v12
	v_exp_f32_e32 v31, v10
	v_pk_mul_f32 v[4:5], v[4:5], v[26:27]
	v_pk_add_f32 v[10:11], v[30:31], 1.0 op_sel_hi:[1,0]
	s_nop 0
	v_div_scale_f32 v12, s[0:1], v11, v11, v6
	v_rcp_f32_e32 v14, v12
	s_nop 0
	v_fma_f32 v15, -v12, v14, 1.0
	v_fmac_f32_e32 v14, v15, v14
	v_div_scale_f32 v15, vcc, v6, v11, v6
	v_mul_f32_e32 v18, v15, v14
	v_fma_f32 v19, -v12, v18, v15
	v_fmac_f32_e32 v18, v19, v14
	v_fma_f32 v12, -v12, v18, v15
	v_div_fmas_f32 v12, v12, v14, v18
	v_div_fixup_f32 v11, v12, v11, v6
	v_div_scale_f32 v6, s[0:1], v10, v10, v2
	v_rcp_f32_e32 v12, v6
	v_and_b32_e32 v19, 0xffff0000, v7
	v_fma_f32 v14, -v6, v12, 1.0
	v_fmac_f32_e32 v12, v14, v12
	v_div_scale_f32 v14, vcc, v2, v10, v2
	v_mul_f32_e32 v15, v14, v12
	v_fma_f32 v18, -v6, v15, v14
	v_fmac_f32_e32 v15, v18, v12
	v_fma_f32 v6, -v6, v15, v14
	v_div_fmas_f32 v6, v6, v12, v15
	v_lshlrev_b32_e32 v18, 16, v7
	v_div_fixup_f32 v10, v6, v10, v2
	v_mul_f32_e32 v6, 0xbfb8aa3b, v18
	v_mul_f32_e32 v7, 0xbfb8aa3b, v19
	v_exp_f32_e32 v6, v6
	v_exp_f32_e32 v7, v7
	v_pk_mul_f32 v[4:5], v[10:11], v[4:5]
	v_pk_mul_f32 v[10:11], v[46:47], v[42:43]
	v_lshlrev_b32_e32 v2, 16, v3
	v_and_b32_e32 v3, 0xffff0000, v3
	v_pk_mul_f32 v[14:15], v[44:45], v[38:39]
	v_pk_mul_f32 v[10:11], v[10:11], v[98:99]
	v_pk_mul_f32 v[2:3], v[40:41], v[2:3]
	v_pk_fma_f32 v[10:11], v[14:15], v[90:91], v[10:11]
	v_pk_add_f32 v[6:7], v[6:7], 1.0 op_sel_hi:[1,0]
	v_pk_fma_f32 v[2:3], v[2:3], v[114:115], v[10:11]
	v_div_scale_f32 v10, s[0:1], v7, v7, v19
	v_rcp_f32_e32 v11, v10
	v_lshlrev_b32_e32 v12, 16, v13
	v_and_b32_e32 v13, 0xffff0000, v13
	v_pk_mul_f32 v[2:3], v[2:3], v[12:13]
	v_fma_f32 v12, -v10, v11, 1.0
	v_fmac_f32_e32 v11, v12, v11
	v_div_scale_f32 v12, vcc, v19, v7, v19
	v_mul_f32_e32 v13, v12, v11
	v_fma_f32 v14, -v10, v13, v12
	v_fmac_f32_e32 v13, v14, v11
	v_fma_f32 v10, -v10, v13, v12
	v_div_fmas_f32 v10, v10, v11, v13
	v_div_fixup_f32 v7, v10, v7, v19
	v_div_scale_f32 v10, s[0:1], v6, v6, v18
	v_rcp_f32_e32 v11, v10
	v_readlane_b32 s0, v251, 59
	v_readlane_b32 s1, v251, 60
	v_add_u32_e32 v39, s34, v72
	v_fma_f32 v12, -v10, v11, 1.0
	v_fmac_f32_e32 v11, v12, v11
	v_div_scale_f32 v12, vcc, v18, v6, v18
	v_mul_f32_e32 v13, v12, v11
	v_fma_f32 v14, -v10, v13, v12
	v_fmac_f32_e32 v13, v14, v11
	v_fma_f32 v10, -v10, v13, v12
	v_div_fmas_f32 v10, v10, v11, v13
	v_div_fixup_f32 v6, v10, v6, v18
	v_pk_mul_f32 v[6:7], v[6:7], v[2:3]
	v_cvt_pk_bf16_f32 v3, v0, v1
	v_lshlrev_b64 v[0:1], 11, v[36:37]
	v_lshl_add_u64 v[0:1], s[0:1], 0, v[0:1]
	s_mov_b32 s0, 0x10ffff
	v_cmp_lt_i32_e32 vcc, s0, v39
	v_cvt_pk_bf16_f32 v2, v28, v29
	v_cvt_pk_bf16_f32 v4, v4, v5
	v_cvt_pk_bf16_f32 v5, v6, v7
	v_lshl_add_u64 v[0:1], v[0:1], 0, v[8:9]
	s_orn2_b64 s[0:1], vcc, exec
	global_store_dwordx4 v[0:1], v[2:5], off

.LBB0_325:
	s_or_b64 exec, exec, s[0:1]
	global_load_dwordx4 v[100:103], v[26:27], off offset:512
	global_load_dwordx4 v[104:107], v[26:27], off offset:1536
	s_nop 0
	s_waitcnt vmcnt(3)
	v_lshlrev_b32_e32 v28, 16, v18
	v_and_b32_e32 v29, 0xffff0000, v18
	s_waitcnt vmcnt(2)
	v_lshlrev_b32_e32 v32, 16, v22
	v_and_b32_e32 v33, 0xffff0000, v22
	v_lshlrev_b32_e32 v62, 16, v19
	v_and_b32_e32 v63, 0xffff0000, v19
	v_lshlrev_b32_e32 v50, 16, v20
	v_and_b32_e32 v51, 0xffff0000, v20
	v_lshlrev_b32_e32 v40, 16, v21
	v_and_b32_e32 v41, 0xffff0000, v21
	v_lshlrev_b32_e32 v18, 16, v4
	v_and_b32_e32 v19, 0xffff0000, v4
	v_lshlrev_b32_e32 v20, 16, v14
	v_and_b32_e32 v21, 0xffff0000, v14
	s_nop 0
	s_nop 0
	v_lshlrev_b32_e32 v68, 16, v23
	v_and_b32_e32 v69, 0xffff0000, v23
	v_lshlrev_b32_e32 v54, 16, v24
	v_and_b32_e32 v55, 0xffff0000, v24
	v_lshlrev_b32_e32 v44, 16, v25
	v_and_b32_e32 v45, 0xffff0000, v25
	v_lshlrev_b32_e32 v72, 16, v10
	v_and_b32_e32 v73, 0xffff0000, v10
	v_lshlrev_b32_e32 v64, 16, v11
	v_and_b32_e32 v65, 0xffff0000, v11
	v_lshlrev_b32_e32 v52, 16, v12
	v_and_b32_e32 v53, 0xffff0000, v12
	v_lshlrev_b32_e32 v42, 16, v13
	v_and_b32_e32 v43, 0xffff0000, v13
	v_lshlrev_b32_e32 v66, 16, v5
	v_and_b32_e32 v67, 0xffff0000, v5
	v_lshlrev_b32_e32 v56, 16, v6
	v_and_b32_e32 v57, 0xffff0000, v6
	v_lshlrev_b32_e32 v46, 16, v7
	v_and_b32_e32 v47, 0xffff0000, v7
	v_lshlrev_b32_e32 v70, 16, v15
	v_and_b32_e32 v71, 0xffff0000, v15
	v_lshlrev_b32_e32 v60, 16, v16
	v_and_b32_e32 v61, 0xffff0000, v16
	v_lshlrev_b32_e32 v48, 16, v17
	v_and_b32_e32 v49, 0xffff0000, v17
	s_waitcnt vmcnt(0)
	v_mov_b64_e32 v[10:11], v[100:101]
	v_mov_b64_e32 v[12:13], v[102:103]
	v_mov_b64_e32 v[4:5], v[104:105]
	v_mov_b64_e32 v[6:7], v[106:107]
	v_pk_mul_f32 v[22:23], v[20:21], v[32:33]
	s_nop 0
	s_nop 0
	s_nop 0
	s_nop 0
	v_pk_mul_f32 v[32:33], v[18:19], v[28:29]
	s_nop 0
	s_nop 0
	s_nop 0
	s_nop 0
	v_lshlrev_b32_e32 v78, 16, v0
	v_and_b32_e32 v79, 0xffff0000, v0
	v_pk_mul_f32 v[72:73], v[72:73], v[78:79]
	v_pk_mul_f32 v[62:63], v[66:67], v[62:63]
	v_ashrrev_i32_e32 v37, 31, v36
	s_waitcnt vmcnt(5)
	v_lshlrev_b32_e32 v80, 16, v10
	s_waitcnt vmcnt(4)
	v_lshlrev_b32_e32 v0, 16, v4
	v_and_b32_e32 v81, 0xffff0000, v10
	v_and_b32_e32 v4, 0xffff0000, v4
	v_mul_f32_e32 v10, 0xbfb8aa3b, v0
	s_waitcnt vmcnt(0)
	v_pk_mul_f32 v[22:23], v[22:23], v[92:93]
	v_exp_f32_e32 v82, v10
	v_pk_fma_f32 v[28:29], v[32:33], v[84:85], v[22:23]
	s_nop 0
	s_nop 0
	s_nop 0
	s_nop 0
	v_mul_f32_e32 v10, 0xbfb8aa3b, v4
	v_exp_f32_e32 v83, v10
	s_waitcnt vmcnt(0)
	v_pk_fma_f32 v[28:29], v[72:73], v[108:109], v[28:29]
	v_pk_add_f32 v[32:33], v[82:83], 1.0 op_sel_hi:[1,0]
	v_pk_mul_f32 v[28:29], v[28:29], v[80:81]
	v_div_scale_f32 v10, s[0:1], v33, v33, v4
	v_rcp_f32_e32 v72, v10
	s_nop 0
	v_fma_f32 v73, -v10, v72, 1.0
	v_fmac_f32_e32 v72, v73, v72
	v_div_scale_f32 v73, vcc, v4, v33, v4
	v_mul_f32_e32 v75, v73, v72
	v_fma_f32 v77, -v10, v75, v73
	v_fmac_f32_e32 v75, v77, v72
	v_fma_f32 v10, -v10, v75, v73
	v_div_fmas_f32 v10, v10, v72, v75
	v_div_fixup_f32 v33, v10, v33, v4
	v_div_scale_f32 v4, s[0:1], v32, v32, v0
	v_rcp_f32_e32 v10, v4
	s_nop 0
	v_fma_f32 v72, -v4, v10, 1.0
	v_fmac_f32_e32 v10, v72, v10
	v_div_scale_f32 v72, vcc, v0, v32, v0
	v_mul_f32_e32 v73, v72, v10
	v_fma_f32 v75, -v4, v73, v72
	v_fmac_f32_e32 v73, v75, v10
	v_fma_f32 v4, -v4, v73, v72
	v_div_fmas_f32 v4, v4, v10, v73
	v_div_fixup_f32 v32, v4, v32, v0
	v_pk_mul_f32 v[28:29], v[28:29], v[32:33]
	v_pk_mul_f32 v[32:33], v[70:71], v[68:69]
	v_lshlrev_b32_e32 v68, 16, v5
	v_and_b32_e32 v69, 0xffff0000, v5
	v_mul_f32_e32 v4, 0xbfb8aa3b, v68
	v_mul_f32_e32 v5, 0xbfb8aa3b, v69
	v_exp_f32_e32 v4, v4
	v_exp_f32_e32 v5, v5
	v_lshlrev_b32_e32 v0, 16, v1
	v_and_b32_e32 v1, 0xffff0000, v1
	v_pk_mul_f32 v[30:31], v[32:33], v[94:95]
	v_pk_mul_f32 v[0:1], v[64:65], v[0:1]
	v_pk_fma_f32 v[26:27], v[62:63], v[86:87], v[30:31]
	v_lshlrev_b32_e32 v10, 16, v11
	v_and_b32_e32 v11, 0xffff0000, v11
	v_pk_fma_f32 v[0:1], v[0:1], v[110:111], v[26:27]
	v_pk_add_f32 v[4:5], v[4:5], 1.0 op_sel_hi:[1,0]
	v_pk_mul_f32 v[0:1], v[0:1], v[10:11]
	v_div_scale_f32 v10, s[0:1], v5, v5, v69
	v_rcp_f32_e32 v11, v10
	v_pk_mul_f32 v[32:33], v[56:57], v[50:51]
	v_add_u32_e32 v72, s34, v39
	v_fma_f32 v26, -v10, v11, 1.0
	v_fmac_f32_e32 v11, v26, v11
	v_div_scale_f32 v26, vcc, v69, v5, v69
	v_mul_f32_e32 v27, v26, v11
	v_fma_f32 v30, -v10, v27, v26
	v_fmac_f32_e32 v27, v30, v11
	v_fma_f32 v10, -v10, v27, v26
	v_div_fmas_f32 v10, v10, v11, v27
	v_div_fixup_f32 v5, v10, v5, v69
	v_div_scale_f32 v10, s[0:1], v4, v4, v68
	v_rcp_f32_e32 v11, v10
	s_nop 0
	v_fma_f32 v26, -v10, v11, 1.0
	v_fmac_f32_e32 v11, v26, v11
	v_div_scale_f32 v26, vcc, v68, v4, v68
	v_mul_f32_e32 v27, v26, v11
	v_fma_f32 v30, -v10, v27, v26
	v_fmac_f32_e32 v27, v30, v11
	v_fma_f32 v10, -v10, v27, v26
	v_div_fmas_f32 v10, v10, v11, v27
	v_div_fixup_f32 v4, v10, v4, v68
	v_pk_mul_f32 v[0:1], v[4:5], v[0:1]
	v_pk_mul_f32 v[4:5], v[60:61], v[54:55]
	v_lshlrev_b32_e32 v10, 16, v2
	v_and_b32_e32 v11, 0xffff0000, v2
	v_pk_mul_f32 v[4:5], v[4:5], v[96:97]
	v_lshlrev_b32_e32 v2, 16, v6
	v_and_b32_e32 v6, 0xffff0000, v6
	v_pk_fma_f32 v[4:5], v[32:33], v[88:89], v[4:5]
	v_pk_mul_f32 v[10:11], v[52:53], v[10:11]
	v_lshlrev_b32_e32 v26, 16, v12
	v_and_b32_e32 v27, 0xffff0000, v12
	v_mul_f32_e32 v12, 0xbfb8aa3b, v2
	v_pk_fma_f32 v[4:5], v[10:11], v[112:113], v[4:5]
	v_mul_f32_e32 v10, 0xbfb8aa3b, v6
	v_exp_f32_e32 v30, v12
	v_exp_f32_e32 v31, v10
	v_pk_mul_f32 v[4:5], v[4:5], v[26:27]
	v_pk_add_f32 v[10:11], v[30:31], 1.0 op_sel_hi:[1,0]
	s_nop 0
	v_div_scale_f32 v12, s[0:1], v11, v11, v6
	v_rcp_f32_e32 v14, v12
	s_nop 0
	v_fma_f32 v15, -v12, v14, 1.0
	v_fmac_f32_e32 v14, v15, v14
	v_div_scale_f32 v15, vcc, v6, v11, v6
	v_mul_f32_e32 v18, v15, v14
	v_fma_f32 v19, -v12, v18, v15
	v_fmac_f32_e32 v18, v19, v14
	v_fma_f32 v12, -v12, v18, v15
	v_div_fmas_f32 v12, v12, v14, v18
	v_div_fixup_f32 v11, v12, v11, v6
	v_div_scale_f32 v6, s[0:1], v10, v10, v2
	v_rcp_f32_e32 v12, v6
	v_and_b32_e32 v19, 0xffff0000, v7
	v_fma_f32 v14, -v6, v12, 1.0
	v_fmac_f32_e32 v12, v14, v12
	v_div_scale_f32 v14, vcc, v2, v10, v2
	v_mul_f32_e32 v15, v14, v12
	v_fma_f32 v18, -v6, v15, v14
	v_fmac_f32_e32 v15, v18, v12
	v_fma_f32 v6, -v6, v15, v14
	v_div_fmas_f32 v6, v6, v12, v15
	v_lshlrev_b32_e32 v18, 16, v7
	v_div_fixup_f32 v10, v6, v10, v2
	v_mul_f32_e32 v6, 0xbfb8aa3b, v18
	v_mul_f32_e32 v7, 0xbfb8aa3b, v19
	v_exp_f32_e32 v6, v6
	v_exp_f32_e32 v7, v7
	v_pk_mul_f32 v[4:5], v[10:11], v[4:5]
	v_pk_mul_f32 v[10:11], v[48:49], v[44:45]
	v_lshlrev_b32_e32 v2, 16, v3
	v_and_b32_e32 v3, 0xffff0000, v3
	v_pk_mul_f32 v[14:15], v[46:47], v[40:41]
	v_pk_mul_f32 v[10:11], v[10:11], v[98:99]
	v_pk_mul_f32 v[2:3], v[42:43], v[2:3]
	v_pk_fma_f32 v[10:11], v[14:15], v[90:91], v[10:11]
	v_pk_add_f32 v[6:7], v[6:7], 1.0 op_sel_hi:[1,0]
	v_pk_fma_f32 v[2:3], v[2:3], v[114:115], v[10:11]
	v_div_scale_f32 v10, s[0:1], v7, v7, v19
	v_rcp_f32_e32 v11, v10
	v_lshlrev_b32_e32 v12, 16, v13
	v_and_b32_e32 v13, 0xffff0000, v13
	v_pk_mul_f32 v[2:3], v[2:3], v[12:13]
	v_fma_f32 v12, -v10, v11, 1.0
	v_fmac_f32_e32 v11, v12, v11
	v_div_scale_f32 v12, vcc, v19, v7, v19
	v_mul_f32_e32 v13, v12, v11
	v_fma_f32 v14, -v10, v13, v12
	v_fmac_f32_e32 v13, v14, v11
	v_fma_f32 v10, -v10, v13, v12
	v_div_fmas_f32 v10, v10, v11, v13
	v_div_fixup_f32 v7, v10, v7, v19
	v_div_scale_f32 v10, s[0:1], v6, v6, v18
	v_rcp_f32_e32 v11, v10
	v_readlane_b32 s0, v251, 59
	v_readlane_b32 s1, v251, 60
	v_cvt_pk_bf16_f32 v4, v4, v5
	v_fma_f32 v12, -v10, v11, 1.0
	v_fmac_f32_e32 v11, v12, v11
	v_div_scale_f32 v12, vcc, v18, v6, v18
	v_mul_f32_e32 v13, v12, v11
	v_fma_f32 v14, -v10, v13, v12
	v_fmac_f32_e32 v13, v14, v11
	v_fma_f32 v10, -v10, v13, v12
	v_div_fmas_f32 v10, v10, v11, v13
	v_div_fixup_f32 v6, v10, v6, v18
	v_pk_mul_f32 v[6:7], v[6:7], v[2:3]
	v_cvt_pk_bf16_f32 v3, v0, v1
	v_lshlrev_b64 v[0:1], 11, v[36:37]
	v_lshl_add_u64 v[0:1], s[0:1], 0, v[0:1]
	s_mov_b32 s0, 0x110000
	v_cvt_pk_bf16_f32 v2, v28, v29
	v_cvt_pk_bf16_f32 v5, v6, v7
	v_lshl_add_u64 v[0:1], v[0:1], 0, v[8:9]
	v_cmp_gt_i32_e32 vcc, s0, v72
	s_mov_b64 s[0:1], -1
	global_store_dwordx4 v[0:1], v[2:5], off
	s_and_saveexec_b64 s[18:19], vcc
	s_cbranch_execz .LBB0_316
	v_ashrrev_i32_e32 v36, 5, v72
	s_mov_b32 s0, 0x8000
	v_cmp_gt_i32_e32 vcc, s0, v36
	v_mov_b64_e32 v[2:3], s[70:71]
	v_mad_i64_i32 v[2:3], s[2:3], v36, s77, v[2:3]
	v_cndmask_b32_e32 v0, v222, v223, vcc
	v_and_b32_e32 v1, v0, v36
	v_mov_b32_e32 v10, 0
	v_cmp_ne_u32_e64 s[0:1], 0, v1
	v_lshl_add_u64 v[26:27], v[2:3], 0, v[8:9]
	v_mov_b32_e32 v4, 0
	v_mov_b32_e32 v5, 0
	v_mov_b32_e32 v6, 0
	v_mov_b32_e32 v7, 0
	s_and_saveexec_b64 s[4:5], s[0:1]
	s_cbranch_execz .LBB0_328
	v_add_co_u32_e32 v2, vcc, 0xfffff000, v26
	s_nop 1
	v_addc_co_u32_e32 v3, vcc, -1, v27, vcc
	global_load_dwordx4 v[4:7], v[2:3], off offset:-3072

.LBB0_367:
	s_or_b64 exec, exec, s[18:19]
	v_add_u32_e32 v69, v5, v79
	v_readlane_b32 s18, v254, 50
	v_lshlrev_b32_e32 v8, 2, v69
	v_readlane_b32 s19, v254, 51
	v_mov_b32_e32 v75, v9
	v_lshl_add_u64 v[62:63], s[18:19], 0, v[8:9]
	s_nop 0
	s_nop 0
	v_add_co_u32_e32 v2, vcc, 0x1000, v62
	s_nop 0
	s_nop 0
	v_addc_co_u32_e32 v3, vcc, 0, v63, vcc
	s_nop 0
	s_nop 0
	s_nop 0
	s_nop 0
	s_nop 0
	s_nop 0
	s_nop 0
	s_nop 0
	s_nop 0
	s_nop 0
	s_nop 0
	s_nop 0
	s_nop 0
	s_nop 0
	s_nop 0
	s_nop 0
	s_nop 0
	v_or_b32_e32 v2, 32, v4
	v_lshlrev_b32_e32 v74, 1, v2
	v_lshl_add_u64 v[60:61], v[0:1], 0, v[74:75]
	v_mov_b32_e32 v4, 0
	v_mov_b32_e32 v0, 0
	v_mov_b32_e32 v1, 0
	v_mov_b32_e32 v2, 0
	v_mov_b32_e32 v3, 0
	s_and_saveexec_b64 s[18:19], s[0:1]
	s_cbranch_execz .LBB0_369
	v_add_co_u32_e32 v0, vcc, 0xfffff000, v60
	s_nop 1
	v_addc_co_u32_e32 v1, vcc, -1, v61, vcc
	global_load_dwordx4 v[0:3], v[0:1], off offset:-3072

.LBB0_371:
	s_or_b64 exec, exec, s[0:1]
	global_load_dword v184, v[186:187], off
	global_load_dword v185, v[188:189], off
	s_waitcnt vmcnt(5)
	v_lshlrev_b32_e32 v64, 16, v22
	v_and_b32_e32 v65, 0xffff0000, v22
	v_lshlrev_b32_e32 v66, 16, v18
	v_and_b32_e32 v67, 0xffff0000, v18
	s_waitcnt vmcnt(5)
	v_pk_mul_f32 v[42:43], v[100:101], v[64:65]
	v_lshlrev_b32_e32 v82, 16, v14
	v_and_b32_e32 v83, 0xffff0000, v14
	s_waitcnt vmcnt(5)
	v_pk_fma_f32 v[42:43], v[84:85], v[66:67], v[42:43]
	s_nop 0
	v_pk_fma_f32 v[42:43], v[120:121], v[82:83], v[42:43]
	s_nop 0
	s_waitcnt vmcnt(3)
	v_pk_add_f32 v[42:43], v[168:169], v[42:43]
	s_nop 0
	v_mul_f32_e32 v8, 0xbfb8aa3b, v42
	v_exp_f32_e32 v46, v8
	v_mul_f32_e32 v8, 0xbfb8aa3b, v43
	v_exp_f32_e32 v47, v8
	s_nop 0
	v_pk_add_f32 v[46:47], v[46:47], 1.0 op_sel_hi:[1,0]
	s_nop 0
	v_div_scale_f32 v8, s[0:1], v47, v47, v43
	v_rcp_f32_e32 v14, v8
	s_nop 0
	v_fma_f32 v18, -v8, v14, 1.0
	v_fmac_f32_e32 v14, v18, v14
	v_div_scale_f32 v18, vcc, v43, v47, v43
	v_mul_f32_e32 v22, v18, v14
	v_fma_f32 v50, -v8, v22, v18
	v_fmac_f32_e32 v22, v50, v14
	v_fma_f32 v8, -v8, v22, v18
	v_div_fmas_f32 v8, v8, v14, v22
	v_div_fixup_f32 v47, v8, v47, v43
	v_div_scale_f32 v8, s[0:1], v46, v46, v42
	v_rcp_f32_e32 v14, v8
	s_nop 0
	v_fma_f32 v18, -v8, v14, 1.0
	v_fmac_f32_e32 v14, v18, v14
	v_div_scale_f32 v18, vcc, v42, v46, v42
	v_mul_f32_e32 v22, v18, v14
	v_fma_f32 v43, -v8, v22, v18
	v_fmac_f32_e32 v22, v43, v14
	v_fma_f32 v8, -v8, v22, v18
	v_div_fmas_f32 v8, v8, v14, v22
	v_lshlrev_b32_e32 v22, 16, v23
	v_and_b32_e32 v23, 0xffff0000, v23
	v_lshlrev_b32_e32 v18, 16, v19
	v_and_b32_e32 v19, 0xffff0000, v19
	v_pk_mul_f32 v[22:23], v[102:103], v[22:23]
	v_lshlrev_b32_e32 v14, 16, v15
	v_and_b32_e32 v15, 0xffff0000, v15
	v_pk_fma_f32 v[18:19], v[86:87], v[18:19], v[22:23]
	v_div_fixup_f32 v46, v8, v46, v42
	v_pk_fma_f32 v[14:15], v[122:123], v[14:15], v[18:19]
	s_waitcnt vmcnt(2)
	v_lshlrev_b32_e32 v52, 16, v7
	v_pk_add_f32 v[14:15], v[170:171], v[14:15]
	s_nop 0
	v_mul_f32_e32 v8, 0xbfb8aa3b, v14
	v_exp_f32_e32 v18, v8
	v_mul_f32_e32 v8, 0xbfb8aa3b, v15
	v_exp_f32_e32 v19, v8
	s_nop 0
	v_pk_add_f32 v[18:19], v[18:19], 1.0 op_sel_hi:[1,0]
	s_nop 0
	v_div_scale_f32 v8, s[0:1], v19, v19, v15
	v_rcp_f32_e32 v22, v8
	s_nop 0
	v_fma_f32 v23, -v8, v22, 1.0
	v_fmac_f32_e32 v22, v23, v22
	v_div_scale_f32 v23, vcc, v15, v19, v15
	v_mul_f32_e32 v42, v23, v22
	v_fma_f32 v43, -v8, v42, v23
	v_fmac_f32_e32 v42, v43, v22
	v_fma_f32 v8, -v8, v42, v23
	v_div_fmas_f32 v8, v8, v22, v42
	v_div_fixup_f32 v45, v8, v19, v15
	v_div_scale_f32 v8, s[0:1], v18, v18, v14
	v_rcp_f32_e32 v15, v8
	s_nop 0
	v_fma_f32 v19, -v8, v15, 1.0
	v_fmac_f32_e32 v15, v19, v15
	v_div_scale_f32 v19, vcc, v14, v18, v14
	v_mul_f32_e32 v22, v19, v15
	v_fma_f32 v23, -v8, v22, v19
	v_fmac_f32_e32 v22, v23, v15
	v_fma_f32 v8, -v8, v22, v19
	v_div_fmas_f32 v8, v8, v15, v22
	v_div_fixup_f32 v44, v8, v18, v14
	v_lshlrev_b32_e32 v14, 16, v24
	v_and_b32_e32 v15, 0xffff0000, v24
	v_lshlrev_b32_e32 v18, 16, v20
	v_and_b32_e32 v19, 0xffff0000, v20
	v_pk_mul_f32 v[14:15], v[104:105], v[14:15]
	v_lshlrev_b32_e32 v22, 16, v16
	v_and_b32_e32 v23, 0xffff0000, v16
	v_pk_fma_f32 v[14:15], v[88:89], v[18:19], v[14:15]
	v_lshlrev_b32_e32 v24, 16, v0
	v_pk_fma_f32 v[14:15], v[124:125], v[22:23], v[14:15]
	s_nop 0
	v_pk_add_f32 v[14:15], v[172:173], v[14:15]
	s_nop 0
	v_mul_f32_e32 v8, 0xbfb8aa3b, v14
	v_exp_f32_e32 v18, v8
	v_mul_f32_e32 v8, 0xbfb8aa3b, v15
	v_exp_f32_e32 v19, v8
	s_nop 0
	v_pk_add_f32 v[18:19], v[18:19], 1.0 op_sel_hi:[1,0]
	s_nop 0
	v_div_scale_f32 v8, s[0:1], v19, v19, v15
	v_rcp_f32_e32 v16, v8
	s_nop 0
	v_fma_f32 v20, -v8, v16, 1.0
	v_fmac_f32_e32 v16, v20, v16
	v_div_scale_f32 v20, vcc, v15, v19, v15
	v_mul_f32_e32 v22, v20, v16
	v_fma_f32 v23, -v8, v22, v20
	v_fmac_f32_e32 v22, v23, v16
	v_fma_f32 v8, -v8, v22, v20
	v_div_fmas_f32 v8, v8, v16, v22
	v_div_fixup_f32 v49, v8, v19, v15
	v_div_scale_f32 v8, s[0:1], v18, v18, v14
	v_rcp_f32_e32 v15, v8
	v_lshlrev_b32_e32 v22, 16, v10
	v_and_b32_e32 v23, 0xffff0000, v10
	v_fma_f32 v16, -v8, v15, 1.0
	v_fmac_f32_e32 v15, v16, v15
	v_div_scale_f32 v16, vcc, v14, v18, v14
	v_mul_f32_e32 v19, v16, v15
	v_fma_f32 v20, -v8, v19, v16
	v_fmac_f32_e32 v19, v20, v15
	v_fma_f32 v8, -v8, v19, v16
	v_div_fmas_f32 v8, v8, v15, v19
	v_div_fixup_f32 v48, v8, v18, v14
	v_lshlrev_b32_e32 v14, 16, v25
	v_and_b32_e32 v15, 0xffff0000, v25
	v_lshlrev_b32_e32 v18, 16, v21
	v_and_b32_e32 v19, 0xffff0000, v21
	v_pk_mul_f32 v[14:15], v[106:107], v[14:15]
	v_lshlrev_b32_e32 v16, 16, v17
	v_and_b32_e32 v17, 0xffff0000, v17
	v_pk_fma_f32 v[14:15], v[90:91], v[18:19], v[14:15]
	v_and_b32_e32 v25, 0xffff0000, v0
	v_pk_fma_f32 v[14:15], v[126:127], v[16:17], v[14:15]
	v_lshlrev_b32_e32 v40, 16, v4
	v_pk_add_f32 v[14:15], v[174:175], v[14:15]
	v_and_b32_e32 v41, 0xffff0000, v4
	v_mul_f32_e32 v8, 0xbfb8aa3b, v14
	v_exp_f32_e32 v16, v8
	v_mul_f32_e32 v8, 0xbfb8aa3b, v15
	v_exp_f32_e32 v17, v8
	s_nop 0
	v_pk_add_f32 v[16:17], v[16:17], 1.0 op_sel_hi:[1,0]
	s_nop 0
	v_div_scale_f32 v8, s[0:1], v17, v17, v15
	v_rcp_f32_e32 v18, v8
	s_nop 0
	v_fma_f32 v19, -v8, v18, 1.0
	v_fmac_f32_e32 v18, v19, v18
	v_div_scale_f32 v19, vcc, v15, v17, v15
	v_mul_f32_e32 v20, v19, v18
	v_fma_f32 v21, -v8, v20, v19
	v_fmac_f32_e32 v20, v21, v18
	v_fma_f32 v8, -v8, v20, v19
	v_div_fmas_f32 v8, v8, v18, v20
	v_div_fixup_f32 v51, v8, v17, v15
	v_div_scale_f32 v8, s[0:1], v16, v16, v14
	v_rcp_f32_e32 v15, v8
	s_nop 0
	v_fma_f32 v17, -v8, v15, 1.0
	v_fmac_f32_e32 v15, v17, v15
	v_div_scale_f32 v17, vcc, v14, v16, v14
	v_mul_f32_e32 v18, v17, v15
	v_fma_f32 v19, -v8, v18, v17
	v_fmac_f32_e32 v18, v19, v15
	v_fma_f32 v8, -v8, v18, v17
	v_div_fmas_f32 v8, v8, v15, v18
	v_div_fixup_f32 v50, v8, v16, v14
	s_nop 0
	v_mov_b64_e32 v[16:17], v[98:99]
	s_nop 0
	s_nop 0
	v_mov_b64_e32 v[18:19], v[112:113]
	v_mov_b64_e32 v[20:21], v[114:115]
	s_nop 0
	v_mov_b64_e32 v[34:35], v[110:111]
	s_nop 0
	s_movk_i32 s0, 0x1000
	v_lshlrev_b32_e32 v8, 16, v3
	s_waitcnt vmcnt(2)
	v_pk_mul_f32 v[22:23], v[108:109], v[22:23]
	s_nop 0
	v_pk_fma_f32 v[22:23], v[92:93], v[24:25], v[22:23]
	v_add_co_u32_e32 v24, vcc, s0, v62
	s_nop 1
	v_addc_co_u32_e32 v25, vcc, 0, v63, vcc
	s_nop 0
	v_mov_b64_e32 v[38:39], v[132:133]
	s_nop 0
	v_mov_b64_e32 v[28:29], v[166:167]
	s_waitcnt vmcnt(2)
	v_pk_fma_f32 v[32:33], v[130:131], v[40:41], v[22:23]
	v_mov_b64_e32 v[22:23], v[180:181]
	v_mov_b64_e32 v[24:25], v[182:183]
	s_nop 0
	v_mov_b64_e32 v[42:43], v[178:179]
	s_waitcnt vmcnt(2)
	v_pk_add_f32 v[32:33], v[176:177], v[32:33]
	s_nop 0
	v_mul_f32_e32 v0, 0xbfb8aa3b, v32
	v_exp_f32_e32 v36, v0
	v_mul_f32_e32 v0, 0xbfb8aa3b, v33
	v_exp_f32_e32 v37, v0
	s_nop 0
	v_pk_add_f32 v[36:37], v[36:37], 1.0 op_sel_hi:[1,0]
	s_nop 0
	v_div_scale_f32 v0, s[0:1], v37, v37, v33
	v_rcp_f32_e32 v4, v0
	s_nop 0
	v_fma_f32 v10, -v0, v4, 1.0
	v_fmac_f32_e32 v4, v10, v4
	v_div_scale_f32 v10, vcc, v33, v37, v33
	v_mul_f32_e32 v40, v10, v4
	v_fma_f32 v41, -v0, v40, v10
	v_fmac_f32_e32 v40, v41, v4
	v_fma_f32 v0, -v0, v40, v10
	v_div_fmas_f32 v0, v0, v4, v40
	v_div_fixup_f32 v33, v0, v37, v33
	v_div_scale_f32 v0, s[0:1], v36, v36, v32
	v_rcp_f32_e32 v4, v0
	s_nop 0
	v_fma_f32 v10, -v0, v4, 1.0
	v_fmac_f32_e32 v4, v10, v4
	v_div_scale_f32 v10, vcc, v32, v36, v32
	v_mul_f32_e32 v37, v10, v4
	v_fma_f32 v40, -v0, v37, v10
	v_fmac_f32_e32 v37, v40, v4
	v_fma_f32 v0, -v0, v37, v10
	v_div_fmas_f32 v0, v0, v4, v37
	v_lshlrev_b32_e32 v10, 16, v11
	v_and_b32_e32 v11, 0xffff0000, v11
	v_div_fixup_f32 v32, v0, v36, v32
	v_lshlrev_b32_e32 v0, 16, v1
	v_and_b32_e32 v1, 0xffff0000, v1
	v_pk_mul_f32 v[10:11], v[110:111], v[10:11]
	v_lshlrev_b32_e32 v4, 16, v5
	v_and_b32_e32 v5, 0xffff0000, v5
	v_pk_fma_f32 v[0:1], v[94:95], v[0:1], v[10:11]
	s_nop 0
	v_pk_fma_f32 v[0:1], v[132:133], v[4:5], v[0:1]
	s_nop 0
	v_pk_add_f32 v[0:1], v[178:179], v[0:1]
	s_nop 0
	v_mul_f32_e32 v4, 0xbfb8aa3b, v0
	v_mul_f32_e32 v5, 0xbfb8aa3b, v1
	v_exp_f32_e32 v4, v4
	v_exp_f32_e32 v5, v5
	s_nop 0
	v_pk_add_f32 v[4:5], v[4:5], 1.0 op_sel_hi:[1,0]
	s_nop 0
	v_div_scale_f32 v10, s[0:1], v5, v5, v1
	v_rcp_f32_e32 v11, v10
	s_nop 0
	v_fma_f32 v30, -v10, v11, 1.0
	v_fmac_f32_e32 v11, v30, v11
	v_div_scale_f32 v30, vcc, v1, v5, v1
	v_mul_f32_e32 v31, v30, v11
	v_fma_f32 v34, -v10, v31, v30
	v_fmac_f32_e32 v31, v34, v11
	v_fma_f32 v10, -v10, v31, v30
	v_div_fmas_f32 v10, v10, v11, v31
	v_div_fixup_f32 v1, v10, v5, v1
	v_div_scale_f32 v5, s[0:1], v4, v4, v0
	v_rcp_f32_e32 v10, v5
	s_nop 0
	v_fma_f32 v11, -v5, v10, 1.0
	v_fmac_f32_e32 v10, v11, v10
	v_div_scale_f32 v11, vcc, v0, v4, v0
	v_mul_f32_e32 v30, v11, v10
	v_fma_f32 v31, -v5, v30, v11
	v_fmac_f32_e32 v30, v31, v10
	v_fma_f32 v5, -v5, v30, v11
	v_div_fmas_f32 v5, v5, v10, v30
	v_div_fixup_f32 v0, v5, v4, v0
	v_lshlrev_b32_e32 v4, 16, v12
	v_and_b32_e32 v5, 0xffff0000, v12
	v_lshlrev_b32_e32 v10, 16, v2
	v_and_b32_e32 v11, 0xffff0000, v2
	v_pk_mul_f32 v[4:5], v[112:113], v[4:5]
	v_lshlrev_b32_e32 v30, 16, v6
	v_and_b32_e32 v31, 0xffff0000, v6
	v_pk_fma_f32 v[4:5], v[96:97], v[10:11], v[4:5]
	s_nop 0
	v_pk_fma_f32 v[4:5], v[164:165], v[30:31], v[4:5]
	s_nop 0
	v_pk_add_f32 v[4:5], v[180:181], v[4:5]
	s_nop 0
	v_mul_f32_e32 v2, 0xbfb8aa3b, v4
	v_exp_f32_e32 v10, v2
	v_mul_f32_e32 v2, 0xbfb8aa3b, v5
	v_exp_f32_e32 v11, v2
	s_nop 0
	v_pk_add_f32 v[10:11], v[10:11], 1.0 op_sel_hi:[1,0]
	s_nop 0
	v_div_scale_f32 v2, s[0:1], v11, v11, v5
	v_rcp_f32_e32 v6, v2
	s_nop 0
	v_fma_f32 v12, -v2, v6, 1.0
	v_fmac_f32_e32 v6, v12, v6
	v_div_scale_f32 v12, vcc, v5, v11, v5
	v_mul_f32_e32 v14, v12, v6
	v_fma_f32 v15, -v2, v14, v12
	v_fmac_f32_e32 v14, v15, v6
	v_fma_f32 v2, -v2, v14, v12
	v_div_fmas_f32 v2, v2, v6, v14
	v_div_fixup_f32 v5, v2, v11, v5
	v_div_scale_f32 v2, s[0:1], v10, v10, v4
	v_rcp_f32_e32 v6, v2
	s_nop 0
	v_fma_f32 v11, -v2, v6, 1.0
	v_fmac_f32_e32 v6, v11, v6
	v_div_scale_f32 v11, vcc, v4, v10, v4
	v_mul_f32_e32 v12, v11, v6
	v_fma_f32 v14, -v2, v12, v11
	v_fmac_f32_e32 v12, v14, v6
	v_fma_f32 v2, -v2, v12, v11
	v_div_fmas_f32 v2, v2, v6, v12
	v_div_fixup_f32 v4, v2, v10, v4
	v_mul_f32_e32 v6, v166, v52
	v_and_b32_e32 v11, 0xffff0000, v7
	v_and_b32_e32 v10, 0xffff0000, v3
	v_mov_b32_e32 v28, v99
	v_pk_mul_f32 v[10:11], v[28:29], v[10:11]
	v_mul_f32_e32 v2, v98, v8
	v_lshlrev_b32_e32 v12, 16, v13
	v_and_b32_e32 v13, 0xffff0000, v13
	v_mov_b32_e32 v3, v10
	v_pk_fma_f32 v[2:3], v[114:115], v[12:13], v[2:3]
	v_mov_b32_e32 v7, v11
	v_pk_add_f32 v[2:3], v[2:3], v[6:7]
	s_nop 0
	v_pk_add_f32 v[2:3], v[182:183], v[2:3]
	s_nop 0
	v_mul_f32_e32 v6, 0xbfb8aa3b, v2
	v_mul_f32_e32 v7, 0xbfb8aa3b, v3
	v_exp_f32_e32 v6, v6
	v_exp_f32_e32 v7, v7
	s_nop 0
	v_pk_add_f32 v[6:7], v[6:7], 1.0 op_sel_hi:[1,0]
	s_nop 0
	v_div_scale_f32 v8, s[0:1], v7, v7, v3
	v_rcp_f32_e32 v10, v8
	s_nop 0
	v_fma_f32 v11, -v8, v10, 1.0
	v_fmac_f32_e32 v10, v11, v10
	v_div_scale_f32 v11, vcc, v3, v7, v3
	v_mul_f32_e32 v12, v11, v10
	v_fma_f32 v13, -v8, v12, v11
	v_fmac_f32_e32 v12, v13, v10
	v_fma_f32 v8, -v8, v12, v11
	v_div_fmas_f32 v8, v8, v10, v12
	v_div_fixup_f32 v3, v8, v7, v3
	v_div_scale_f32 v7, s[0:1], v6, v6, v2
	v_rcp_f32_e32 v8, v7
	s_nop 0
	v_fma_f32 v10, -v7, v8, 1.0
	v_fmac_f32_e32 v8, v10, v8
	v_div_scale_f32 v10, vcc, v2, v6, v2
	v_mul_f32_e32 v11, v10, v8
	v_fma_f32 v12, -v7, v11, v10
	v_fmac_f32_e32 v11, v12, v8
	v_fma_f32 v7, -v7, v11, v10
	v_div_fmas_f32 v7, v7, v8, v11
	v_div_fixup_f32 v2, v7, v6, v2
	s_and_saveexec_b64 s[0:1], s[6:7]
	s_cbranch_execz .LBB0_373
	v_and_b32_e32 v6, 4, v78
	v_lshrrev_b32_e32 v7, 6, v80
	v_cmp_eq_u32_e32 vcc, 0, v6
	s_nop 1
	v_cndmask_b32_e32 v6, v80, v7, vcc
	v_lshlrev_b32_e32 v6, 8, v6
	v_and_b32_e32 v6, 0x3f00, v6
	v_lshlrev_b32_e32 v7, 3, v79
	v_add3_u32 v6, 0, v6, v7
	ds_read_b128 v[10:13], v6
	ds_read_b128 v[14:17], v6 offset:16
	ds_read_b128 v[18:21], v6 offset:32
	ds_read_b128 v[22:25], v6 offset:48
	s_waitcnt lgkmcnt(3)
	v_mov_b32_e32 v7, v12
	v_mov_b32_e32 v12, v11
	v_mov_b32_e32 v6, v10
	v_pk_mul_f32 v[10:11], v[32:33], v[12:13]
	s_waitcnt lgkmcnt(0)
	v_mov_b32_e32 v8, v23
	v_pk_fma_f32 v[10:11], v[46:47], v[6:7], v[10:11] neg_lo:[0,0,1] neg_hi:[0,0,1]
	v_pk_mul_f32 v[6:7], v[32:33], v[6:7]
	s_nop 0
	v_pk_fma_f32 v[32:33], v[46:47], v[12:13], v[6:7]
	v_mov_b32_e32 v7, v16
	v_mov_b32_e32 v16, v15
	v_mov_b32_e32 v6, v14
	v_pk_mul_f32 v[12:13], v[0:1], v[16:17]
	v_pk_mul_f32 v[0:1], v[0:1], v[6:7]
	v_pk_fma_f32 v[12:13], v[44:45], v[6:7], v[12:13] neg_lo:[0,0,1] neg_hi:[0,0,1]
	v_mov_b32_e32 v6, v18
	v_mov_b32_e32 v7, v20
	v_mov_b32_e32 v20, v19
	v_pk_mul_f32 v[14:15], v[4:5], v[20:21]
	v_pk_mul_f32 v[4:5], v[4:5], v[6:7]
	v_pk_fma_f32 v[0:1], v[44:45], v[16:17], v[0:1]
	v_pk_fma_f32 v[4:5], v[48:49], v[20:21], v[4:5]
	v_pk_mul_f32 v[16:17], v[2:3], v[8:9]
	v_pk_mul_f32 v[20:21], v[2:3], v[22:23]
	v_mov_b32_e32 v2, v51
	v_pk_fma_f32 v[14:15], v[48:49], v[6:7], v[14:15] neg_lo:[0,0,1] neg_hi:[0,0,1]
	v_pk_mul_f32 v[6:7], v[50:51], v[22:23]
	v_pk_mul_f32 v[18:19], v[50:51], v[8:9]
	v_pk_mul_f32 v[22:23], v[2:3], v[24:25]
	v_mov_b32_e32 v50, v3
	v_mov_b32_e32 v7, v22
	v_mov_b32_e32 v17, v23
	v_pk_mul_f32 v[2:3], v[50:51], v[24:25]
	v_pk_add_f32 v[6:7], v[6:7], v[16:17] neg_lo:[0,1] neg_hi:[0,1]
	v_mov_b32_e32 v19, v3
	v_mov_b32_e32 v21, v2
	v_pk_add_f32 v[2:3], v[18:19], v[20:21]
	v_mov_b64_e32 v[50:51], v[6:7]
	v_mov_b32_e32 v46, v10
	v_mov_b32_e32 v47, v11
	v_mov_b32_e32 v44, v12
	v_mov_b32_e32 v45, v13
	v_mov_b32_e32 v48, v14
	v_mov_b32_e32 v49, v15

.LBB0_378:
	s_or_b64 exec, exec, s[24:25]
	s_nop 0
	s_nop 0
	s_nop 0
	s_nop 0
	s_nop 0
	s_nop 0
	s_nop 0
	s_nop 0
	s_nop 0
	s_nop 0
	s_nop 0
	s_nop 0
	s_nop 0
	s_nop 0
	s_nop 0
	s_nop 0
	v_mov_b32_e32 v75, v9
	v_lshl_add_u64 v[68:69], v[0:1], 0, v[74:75]
	v_mov_b32_e32 v4, 0
	v_mov_b32_e32 v0, 0
	v_mov_b32_e32 v1, 0
	v_mov_b32_e32 v2, 0
	v_mov_b32_e32 v3, 0
	s_and_saveexec_b64 s[24:25], s[0:1]
	s_cbranch_execz .LBB0_380
	v_add_co_u32_e32 v0, vcc, 0xfffff000, v68
	s_nop 1
	v_addc_co_u32_e32 v1, vcc, -1, v69, vcc
	global_load_dwordx4 v[0:3], v[0:1], off offset:-3072

.LBB0_382:
	s_or_b64 exec, exec, s[0:1]
	global_load_dword v184, v[186:187], off
	global_load_dword v185, v[188:189], off
	s_waitcnt vmcnt(5)
	v_lshlrev_b32_e32 v68, 16, v22
	v_and_b32_e32 v69, 0xffff0000, v22
	v_lshlrev_b32_e32 v70, 16, v18
	v_and_b32_e32 v71, 0xffff0000, v18
	s_waitcnt vmcnt(5)
	v_pk_mul_f32 v[54:55], v[100:101], v[68:69]
	v_lshlrev_b32_e32 v72, 16, v14
	v_and_b32_e32 v73, 0xffff0000, v14
	v_pk_fma_f32 v[42:43], v[84:85], v[70:71], v[54:55]
	s_waitcnt vmcnt(5)
	v_pk_fma_f32 v[42:43], v[120:121], v[72:73], v[42:43]
	s_waitcnt vmcnt(3)
	v_pk_add_f32 v[42:43], v[168:169], v[42:43]
	s_nop 0
	v_mul_f32_e32 v14, 0xbfb8aa3b, v42
	v_exp_f32_e32 v46, v14
	v_mul_f32_e32 v14, 0xbfb8aa3b, v43
	v_exp_f32_e32 v47, v14
	s_nop 0
	v_pk_add_f32 v[46:47], v[46:47], 1.0 op_sel_hi:[1,0]
	s_nop 0
	v_div_scale_f32 v14, s[0:1], v47, v47, v43
	v_rcp_f32_e32 v18, v14
	s_nop 0
	v_fma_f32 v22, -v14, v18, 1.0
	v_fmac_f32_e32 v18, v22, v18
	v_div_scale_f32 v22, vcc, v43, v47, v43
	v_mul_f32_e32 v50, v22, v18
	v_fma_f32 v51, -v14, v50, v22
	v_fmac_f32_e32 v50, v51, v18
	v_fma_f32 v14, -v14, v50, v22
	v_div_fmas_f32 v14, v14, v18, v50
	v_div_fixup_f32 v47, v14, v47, v43
	v_div_scale_f32 v14, s[0:1], v46, v46, v42
	v_rcp_f32_e32 v18, v14
	s_nop 0
	v_fma_f32 v22, -v14, v18, 1.0
	v_fmac_f32_e32 v18, v22, v18
	v_div_scale_f32 v22, vcc, v42, v46, v42
	v_mul_f32_e32 v43, v22, v18
	v_fma_f32 v50, -v14, v43, v22
	v_fmac_f32_e32 v43, v50, v18
	v_fma_f32 v14, -v14, v43, v22
	v_lshlrev_b32_e32 v22, 16, v23
	v_and_b32_e32 v23, 0xffff0000, v23
	v_div_fmas_f32 v14, v14, v18, v43
	v_lshlrev_b32_e32 v18, 16, v19
	v_and_b32_e32 v19, 0xffff0000, v19
	v_pk_mul_f32 v[22:23], v[102:103], v[22:23]
	v_div_fixup_f32 v46, v14, v46, v42
	v_lshlrev_b32_e32 v14, 16, v15
	v_and_b32_e32 v15, 0xffff0000, v15
	v_pk_fma_f32 v[18:19], v[86:87], v[18:19], v[22:23]
	s_nop 0
	v_pk_fma_f32 v[14:15], v[122:123], v[14:15], v[18:19]
	s_nop 0
	v_pk_add_f32 v[14:15], v[170:171], v[14:15]
	s_waitcnt vmcnt(2)
	v_lshlrev_b32_e32 v53, 16, v7
	v_mul_f32_e32 v18, 0xbfb8aa3b, v14
	v_mul_f32_e32 v19, 0xbfb8aa3b, v15
	v_exp_f32_e32 v18, v18
	v_exp_f32_e32 v19, v19
	v_lshlrev_b32_e32 v52, 16, v3
	v_pk_add_f32 v[18:19], v[18:19], 1.0 op_sel_hi:[1,0]
	s_nop 0
	v_div_scale_f32 v22, s[0:1], v19, v19, v15
	v_rcp_f32_e32 v23, v22
	s_nop 0
	v_fma_f32 v42, -v22, v23, 1.0
	v_fmac_f32_e32 v23, v42, v23
	v_div_scale_f32 v42, vcc, v15, v19, v15
	v_mul_f32_e32 v43, v42, v23
	v_fma_f32 v44, -v22, v43, v42
	v_fmac_f32_e32 v43, v44, v23
	v_fma_f32 v22, -v22, v43, v42
	v_div_fmas_f32 v22, v22, v23, v43
	v_div_fixup_f32 v45, v22, v19, v15
	v_div_scale_f32 v15, s[0:1], v18, v18, v14
	v_rcp_f32_e32 v19, v15
	s_nop 0
	v_fma_f32 v22, -v15, v19, 1.0
	v_fmac_f32_e32 v19, v22, v19
	v_div_scale_f32 v22, vcc, v14, v18, v14
	v_mul_f32_e32 v23, v22, v19
	v_fma_f32 v42, -v15, v23, v22
	v_fmac_f32_e32 v23, v42, v19
	v_fma_f32 v15, -v15, v23, v22
	v_div_fmas_f32 v15, v15, v19, v23
	v_div_fixup_f32 v44, v15, v18, v14
	v_lshlrev_b32_e32 v14, 16, v24
	v_and_b32_e32 v15, 0xffff0000, v24
	v_lshlrev_b32_e32 v18, 16, v20
	v_and_b32_e32 v19, 0xffff0000, v20
	v_pk_mul_f32 v[14:15], v[104:105], v[14:15]
	v_lshlrev_b32_e32 v22, 16, v16
	v_and_b32_e32 v23, 0xffff0000, v16
	v_pk_fma_f32 v[14:15], v[88:89], v[18:19], v[14:15]
	v_lshlrev_b32_e32 v26, 16, v4
	v_pk_fma_f32 v[14:15], v[124:125], v[22:23], v[14:15]
	v_and_b32_e32 v27, 0xffff0000, v4
	v_pk_add_f32 v[14:15], v[172:173], v[14:15]
	s_nop 0
	v_mul_f32_e32 v16, 0xbfb8aa3b, v14
	v_exp_f32_e32 v18, v16
	v_mul_f32_e32 v16, 0xbfb8aa3b, v15
	v_exp_f32_e32 v19, v16
	s_nop 0
	v_pk_add_f32 v[18:19], v[18:19], 1.0 op_sel_hi:[1,0]
	s_nop 0
	v_div_scale_f32 v16, s[0:1], v19, v19, v15
	v_rcp_f32_e32 v20, v16
	s_nop 0
	v_fma_f32 v22, -v16, v20, 1.0
	v_fmac_f32_e32 v20, v22, v20
	v_div_scale_f32 v22, vcc, v15, v19, v15
	v_mul_f32_e32 v23, v22, v20
	v_fma_f32 v24, -v16, v23, v22
	v_fmac_f32_e32 v23, v24, v20
	v_fma_f32 v16, -v16, v23, v22
	v_div_fmas_f32 v16, v16, v20, v23
	v_div_fixup_f32 v49, v16, v19, v15
	v_div_scale_f32 v15, s[0:1], v18, v18, v14
	v_rcp_f32_e32 v16, v15
	v_and_b32_e32 v23, 0xffff0000, v10
	v_lshlrev_b32_e32 v24, 16, v0
	v_fma_f32 v19, -v15, v16, 1.0
	v_fmac_f32_e32 v16, v19, v16
	v_div_scale_f32 v19, vcc, v14, v18, v14
	v_mul_f32_e32 v20, v19, v16
	v_fma_f32 v22, -v15, v20, v19
	v_fmac_f32_e32 v20, v22, v16
	v_fma_f32 v15, -v15, v20, v19
	v_div_fmas_f32 v15, v15, v16, v20
	v_div_fixup_f32 v48, v15, v18, v14
	v_lshlrev_b32_e32 v14, 16, v25
	v_and_b32_e32 v15, 0xffff0000, v25
	v_lshlrev_b32_e32 v18, 16, v21
	v_and_b32_e32 v19, 0xffff0000, v21
	v_pk_mul_f32 v[14:15], v[106:107], v[14:15]
	v_lshlrev_b32_e32 v16, 16, v17
	v_and_b32_e32 v17, 0xffff0000, v17
	v_pk_fma_f32 v[14:15], v[90:91], v[18:19], v[14:15]
	v_and_b32_e32 v25, 0xffff0000, v0
	v_pk_fma_f32 v[14:15], v[126:127], v[16:17], v[14:15]
	s_nop 0
	v_pk_add_f32 v[14:15], v[174:175], v[14:15]
	s_nop 0
	v_mul_f32_e32 v16, 0xbfb8aa3b, v14
	v_mul_f32_e32 v17, 0xbfb8aa3b, v15
	v_exp_f32_e32 v16, v16
	v_exp_f32_e32 v17, v17
	s_nop 0
	v_pk_add_f32 v[16:17], v[16:17], 1.0 op_sel_hi:[1,0]
	s_nop 0
	v_div_scale_f32 v18, s[0:1], v17, v17, v15
	v_rcp_f32_e32 v19, v18
	s_nop 0
	v_fma_f32 v20, -v18, v19, 1.0
	v_fmac_f32_e32 v19, v20, v19
	v_div_scale_f32 v20, vcc, v15, v17, v15
	v_mul_f32_e32 v21, v20, v19
	v_fma_f32 v22, -v18, v21, v20
	v_fmac_f32_e32 v21, v22, v19
	v_fma_f32 v18, -v18, v21, v20
	v_div_fmas_f32 v18, v18, v19, v21
	v_div_fixup_f32 v51, v18, v17, v15
	v_div_scale_f32 v15, s[0:1], v16, v16, v14
	v_rcp_f32_e32 v17, v15
	v_lshlrev_b32_e32 v22, 16, v10
	v_fma_f32 v18, -v15, v17, 1.0
	v_fmac_f32_e32 v17, v18, v17
	v_div_scale_f32 v18, vcc, v14, v16, v14
	v_mul_f32_e32 v19, v18, v17
	v_fma_f32 v20, -v15, v19, v18
	v_fmac_f32_e32 v19, v20, v17
	v_fma_f32 v15, -v15, v19, v18
	v_div_fmas_f32 v15, v15, v17, v19
	v_div_fixup_f32 v50, v15, v16, v14
	v_mov_b64_e32 v[18:19], v[96:97]
	v_mov_b64_e32 v[20:21], v[98:99]
	s_nop 0
	s_nop 0
	s_nop 0
	v_mov_b64_e32 v[16:17], v[114:115]
	s_nop 0
	v_mov_b64_e32 v[34:35], v[110:111]
	s_waitcnt vmcnt(2)
	v_pk_mul_f32 v[22:23], v[108:109], v[22:23]
	s_nop 0
	v_pk_fma_f32 v[28:29], v[92:93], v[24:25], v[22:23]
	v_mov_b64_e32 v[22:23], v[164:165]
	v_mov_b64_e32 v[24:25], v[166:167]
	s_nop 0
	v_mov_b64_e32 v[38:39], v[132:133]
	s_waitcnt vmcnt(2)
	v_pk_fma_f32 v[32:33], v[130:131], v[26:27], v[28:29]
	s_nop 0
	s_nop 0
	s_nop 0
	v_mov_b64_e32 v[42:43], v[178:179]
	s_waitcnt vmcnt(2)
	v_pk_add_f32 v[32:33], v[176:177], v[32:33]
	s_nop 0
	v_mul_f32_e32 v0, 0xbfb8aa3b, v32
	v_exp_f32_e32 v36, v0
	v_mul_f32_e32 v0, 0xbfb8aa3b, v33
	v_exp_f32_e32 v37, v0
	s_nop 0
	v_pk_add_f32 v[36:37], v[36:37], 1.0 op_sel_hi:[1,0]
	s_nop 0
	v_div_scale_f32 v0, s[0:1], v37, v37, v33
	v_rcp_f32_e32 v4, v0
	s_nop 0
	v_fma_f32 v10, -v0, v4, 1.0
	v_fmac_f32_e32 v4, v10, v4
	v_div_scale_f32 v10, vcc, v33, v37, v33
	v_mul_f32_e32 v40, v10, v4
	v_fma_f32 v41, -v0, v40, v10
	v_fmac_f32_e32 v40, v41, v4
	v_fma_f32 v0, -v0, v40, v10
	v_div_fmas_f32 v0, v0, v4, v40
	v_div_fixup_f32 v33, v0, v37, v33
	v_div_scale_f32 v0, s[0:1], v36, v36, v32
	v_rcp_f32_e32 v4, v0
	s_nop 0
	v_fma_f32 v10, -v0, v4, 1.0
	v_fmac_f32_e32 v4, v10, v4
	v_div_scale_f32 v10, vcc, v32, v36, v32
	v_mul_f32_e32 v37, v10, v4
	v_fma_f32 v40, -v0, v37, v10
	v_fmac_f32_e32 v37, v40, v4
	v_fma_f32 v0, -v0, v37, v10
	v_div_fmas_f32 v0, v0, v4, v37
	v_lshlrev_b32_e32 v10, 16, v11
	v_and_b32_e32 v11, 0xffff0000, v11
	v_div_fixup_f32 v32, v0, v36, v32
	v_lshlrev_b32_e32 v0, 16, v1
	v_and_b32_e32 v1, 0xffff0000, v1
	v_pk_mul_f32 v[10:11], v[110:111], v[10:11]
	v_lshlrev_b32_e32 v4, 16, v5
	v_and_b32_e32 v5, 0xffff0000, v5
	v_pk_fma_f32 v[0:1], v[94:95], v[0:1], v[10:11]
	s_nop 0
	v_pk_fma_f32 v[0:1], v[132:133], v[4:5], v[0:1]
	s_nop 0
	v_pk_add_f32 v[0:1], v[178:179], v[0:1]
	s_nop 0
	v_mul_f32_e32 v4, 0xbfb8aa3b, v0
	v_mul_f32_e32 v5, 0xbfb8aa3b, v1
	v_exp_f32_e32 v4, v4
	v_exp_f32_e32 v5, v5
	s_nop 0
	v_pk_add_f32 v[4:5], v[4:5], 1.0 op_sel_hi:[1,0]
	s_nop 0
	v_div_scale_f32 v10, s[0:1], v5, v5, v1
	v_rcp_f32_e32 v11, v10
	s_nop 0
	v_fma_f32 v30, -v10, v11, 1.0
	v_fmac_f32_e32 v11, v30, v11
	v_div_scale_f32 v30, vcc, v1, v5, v1
	v_mul_f32_e32 v31, v30, v11
	v_fma_f32 v34, -v10, v31, v30
	v_fmac_f32_e32 v31, v34, v11
	v_fma_f32 v10, -v10, v31, v30
	v_div_fmas_f32 v10, v10, v11, v31
	v_div_fixup_f32 v1, v10, v5, v1
	v_div_scale_f32 v5, s[0:1], v4, v4, v0
	v_rcp_f32_e32 v10, v5
	s_nop 0
	v_fma_f32 v11, -v5, v10, 1.0
	v_fmac_f32_e32 v10, v11, v10
	v_div_scale_f32 v11, vcc, v0, v4, v0
	v_mul_f32_e32 v30, v11, v10
	v_fma_f32 v31, -v5, v30, v11
	v_fmac_f32_e32 v30, v31, v10
	v_fma_f32 v5, -v5, v30, v11
	v_div_fmas_f32 v5, v5, v10, v30
	v_div_fixup_f32 v0, v5, v4, v0
	v_lshlrev_b32_e32 v4, 16, v12
	v_and_b32_e32 v5, 0xffff0000, v12
	v_lshlrev_b32_e32 v10, 16, v2
	v_and_b32_e32 v11, 0xffff0000, v2
	v_pk_mul_f32 v[4:5], v[112:113], v[4:5]
	v_lshlrev_b32_e32 v30, 16, v6
	v_and_b32_e32 v31, 0xffff0000, v6
	v_pk_fma_f32 v[4:5], v[96:97], v[10:11], v[4:5]
	s_nop 0
	v_pk_fma_f32 v[4:5], v[164:165], v[30:31], v[4:5]
	s_nop 0
	v_pk_add_f32 v[4:5], v[180:181], v[4:5]
	s_nop 0
	v_mul_f32_e32 v2, 0xbfb8aa3b, v4
	v_exp_f32_e32 v10, v2
	v_mul_f32_e32 v2, 0xbfb8aa3b, v5
	v_exp_f32_e32 v11, v2
	s_nop 0
	v_pk_add_f32 v[10:11], v[10:11], 1.0 op_sel_hi:[1,0]
	s_nop 0
	v_div_scale_f32 v2, s[0:1], v11, v11, v5
	v_rcp_f32_e32 v6, v2
	s_nop 0
	v_fma_f32 v12, -v2, v6, 1.0
	v_fmac_f32_e32 v6, v12, v6
	v_div_scale_f32 v12, vcc, v5, v11, v5
	v_mul_f32_e32 v14, v12, v6
	v_fma_f32 v15, -v2, v14, v12
	v_fmac_f32_e32 v14, v15, v6
	v_fma_f32 v2, -v2, v14, v12
	v_div_fmas_f32 v2, v2, v6, v14
	v_div_fixup_f32 v5, v2, v11, v5
	v_div_scale_f32 v2, s[0:1], v10, v10, v4
	v_rcp_f32_e32 v6, v2
	s_nop 0
	v_fma_f32 v11, -v2, v6, 1.0
	v_fmac_f32_e32 v6, v11, v6
	v_div_scale_f32 v11, vcc, v4, v10, v4
	v_mul_f32_e32 v12, v11, v6
	v_fma_f32 v14, -v2, v12, v11
	v_fmac_f32_e32 v12, v14, v6
	v_fma_f32 v2, -v2, v12, v11
	v_div_fmas_f32 v2, v2, v6, v12
	v_div_fixup_f32 v4, v2, v10, v4
	v_mul_f32_e32 v6, v166, v53
	v_and_b32_e32 v11, 0xffff0000, v7
	v_and_b32_e32 v10, 0xffff0000, v3
	v_mov_b32_e32 v24, v99
	v_pk_mul_f32 v[10:11], v[24:25], v[10:11]
	v_mul_f32_e32 v2, v98, v52
	v_lshlrev_b32_e32 v12, 16, v13
	v_and_b32_e32 v13, 0xffff0000, v13
	v_mov_b32_e32 v3, v10
	v_pk_fma_f32 v[2:3], v[114:115], v[12:13], v[2:3]
	v_mov_b32_e32 v7, v11
	v_pk_add_f32 v[2:3], v[2:3], v[6:7]
	s_nop 0
	v_pk_add_f32 v[2:3], v[182:183], v[2:3]
	s_nop 0
	v_mul_f32_e32 v6, 0xbfb8aa3b, v2
	v_mul_f32_e32 v7, 0xbfb8aa3b, v3
	v_exp_f32_e32 v6, v6
	v_exp_f32_e32 v7, v7
	s_nop 0
	v_pk_add_f32 v[6:7], v[6:7], 1.0 op_sel_hi:[1,0]
	s_nop 0
	v_div_scale_f32 v10, s[0:1], v7, v7, v3
	v_rcp_f32_e32 v11, v10
	s_nop 0
	v_fma_f32 v12, -v10, v11, 1.0
	v_fmac_f32_e32 v11, v12, v11
	v_div_scale_f32 v12, vcc, v3, v7, v3
	v_mul_f32_e32 v13, v12, v11
	v_fma_f32 v14, -v10, v13, v12
	v_fmac_f32_e32 v13, v14, v11
	v_fma_f32 v10, -v10, v13, v12
	v_div_fmas_f32 v10, v10, v11, v13
	v_div_fixup_f32 v3, v10, v7, v3
	v_div_scale_f32 v7, s[0:1], v6, v6, v2
	v_rcp_f32_e32 v10, v7
	s_nop 0
	v_fma_f32 v11, -v7, v10, 1.0
	v_fmac_f32_e32 v10, v11, v10
	v_div_scale_f32 v11, vcc, v2, v6, v2
	v_mul_f32_e32 v12, v11, v10
	v_fma_f32 v13, -v7, v12, v11
	v_fmac_f32_e32 v12, v13, v10
	v_fma_f32 v7, -v7, v12, v11
	v_div_fmas_f32 v7, v7, v10, v12
	v_div_fixup_f32 v2, v7, v6, v2
	s_and_saveexec_b64 s[0:1], s[6:7]
	s_cbranch_execz .LBB0_361
	v_and_b32_e32 v6, 4, v78
	v_lshrrev_b32_e32 v7, 6, v81
	v_cmp_eq_u32_e32 vcc, 0, v6
	s_nop 1
	v_cndmask_b32_e32 v6, v81, v7, vcc
	v_lshlrev_b32_e32 v6, 8, v6
	v_and_b32_e32 v6, 0x3f00, v6
	v_lshlrev_b32_e32 v7, 3, v79
	v_add3_u32 v6, 0, v6, v7
	ds_read_b128 v[10:13], v6
	ds_read_b128 v[14:17], v6 offset:16
	ds_read_b128 v[18:21], v6 offset:32
	ds_read_b128 v[22:25], v6 offset:48
	s_waitcnt lgkmcnt(3)
	v_mov_b32_e32 v7, v12
	v_mov_b32_e32 v12, v11
	v_mov_b32_e32 v6, v10
	v_pk_mul_f32 v[10:11], v[32:33], v[12:13]
	s_nop 0
	v_pk_fma_f32 v[10:11], v[46:47], v[6:7], v[10:11] neg_lo:[0,0,1] neg_hi:[0,0,1]
	v_pk_mul_f32 v[6:7], v[32:33], v[6:7]
	s_nop 0
	v_pk_fma_f32 v[32:33], v[46:47], v[12:13], v[6:7]
	s_waitcnt lgkmcnt(2)
	v_mov_b32_e32 v7, v16
	v_mov_b32_e32 v16, v15
	v_mov_b32_e32 v6, v14
	v_pk_mul_f32 v[12:13], v[0:1], v[16:17]
	v_pk_mul_f32 v[0:1], v[0:1], v[6:7]
	v_pk_fma_f32 v[12:13], v[44:45], v[6:7], v[12:13] neg_lo:[0,0,1] neg_hi:[0,0,1]
	s_waitcnt lgkmcnt(1)
	v_mov_b32_e32 v6, v18
	v_mov_b32_e32 v7, v20
	v_mov_b32_e32 v20, v19
	v_pk_fma_f32 v[0:1], v[44:45], v[16:17], v[0:1]
	v_pk_mul_f32 v[14:15], v[4:5], v[20:21]
	v_pk_mul_f32 v[4:5], v[4:5], v[6:7]
	s_waitcnt lgkmcnt(0)
	v_mov_b32_e32 v16, v23
	v_pk_fma_f32 v[4:5], v[48:49], v[20:21], v[4:5]
	v_pk_mul_f32 v[18:19], v[2:3], v[16:17]
	v_pk_mul_f32 v[20:21], v[2:3], v[22:23]
	v_mov_b32_e32 v2, v51
	v_pk_fma_f32 v[14:15], v[48:49], v[6:7], v[14:15] neg_lo:[0,0,1] neg_hi:[0,0,1]
	v_pk_mul_f32 v[6:7], v[50:51], v[22:23]
	v_pk_mul_f32 v[16:17], v[50:51], v[16:17]
	v_pk_mul_f32 v[22:23], v[2:3], v[24:25]
	v_mov_b32_e32 v50, v3
	v_mov_b32_e32 v7, v22
	v_mov_b32_e32 v19, v23
	v_pk_mul_f32 v[2:3], v[50:51], v[24:25]
	v_pk_add_f32 v[6:7], v[6:7], v[18:19] neg_lo:[0,1] neg_hi:[0,1]
	v_mov_b32_e32 v17, v3
	v_mov_b32_e32 v21, v2
	v_pk_add_f32 v[2:3], v[16:17], v[20:21]
	v_mov_b64_e32 v[50:51], v[6:7]
	v_mov_b32_e32 v46, v10
	v_mov_b32_e32 v47, v11
	v_mov_b32_e32 v44, v12
	v_mov_b32_e32 v45, v13
	v_mov_b32_e32 v48, v14
	v_mov_b32_e32 v49, v15
	s_branch .LBB0_361
